# RWKV scan: P1 (rcp+Newton, wave-uniform branch) and P2 (interleaved DPP reductions, batched bonus store) rewritten by hand; step loop hand-scheduled; GEMM K-loops lean LDS-DMA issue
# speedup vs baseline: 1.0226x; 1.0226x over previous
.LBB0_1600:
	s_waitcnt vmcnt(27)
	v_mfma_f32_32x32x16_bf16 v[0:15], v[32:35], v[16:19], 0
	s_waitcnt vmcnt(26)
	v_mfma_f32_32x32x16_bf16 v[0:15], v[36:39], v[20:23], v[0:15]
	s_waitcnt vmcnt(25)
	v_mfma_f32_32x32x16_bf16 v[0:15], v[40:43], v[24:27], v[0:15]
	s_waitcnt vmcnt(24)
	v_mfma_f32_32x32x16_bf16 v[0:15], v[44:47], v[28:31], v[0:15]
	s_nop 11
	s_and_b64 vcc, exec, s[4:5]
	s_cbranch_vccz .Lrw_p1_decay
	v_add_f32_e32 v48, v176, v0
	v_add_f32_e32 v49, v176, v1
	v_max_f32_e32 v48, 0xc2a00000, v48
	v_max_f32_e32 v49, 0xc2a00000, v49
	v_mul_f32_e32 v48, 0xbfb8aa3b, v48
	v_mul_f32_e32 v49, 0xbfb8aa3b, v49
	v_exp_f32_e32 v48, v48
	v_exp_f32_e32 v49, v49
	v_add_f32_e32 v50, 1.0, v48
	v_add_f32_e32 v51, 1.0, v49
	v_rcp_f32_e32 v52, v50
	v_rcp_f32_e32 v53, v51
	v_fma_f32 v54, -v50, v52, 1.0
	v_fma_f32 v55, -v51, v53, 1.0
	v_fma_f32 v52, v52, v54, v52
	v_fma_f32 v53, v53, v55, v53
	ds_write_b32 v171, v52
	ds_write_b32 v171, v53 offset:256
	v_add_f32_e32 v48, v176, v2
	v_add_f32_e32 v49, v176, v3
	v_max_f32_e32 v48, 0xc2a00000, v48
	v_max_f32_e32 v49, 0xc2a00000, v49
	v_mul_f32_e32 v48, 0xbfb8aa3b, v48
	v_mul_f32_e32 v49, 0xbfb8aa3b, v49
	v_exp_f32_e32 v48, v48
	v_exp_f32_e32 v49, v49
	v_add_f32_e32 v50, 1.0, v48
	v_add_f32_e32 v51, 1.0, v49
	v_rcp_f32_e32 v52, v50
	v_rcp_f32_e32 v53, v51
	v_fma_f32 v54, -v50, v52, 1.0
	v_fma_f32 v55, -v51, v53, 1.0
	v_fma_f32 v52, v52, v54, v52
	v_fma_f32 v53, v53, v55, v53
	ds_write_b32 v171, v52 offset:512
	ds_write_b32 v171, v53 offset:768
	v_add_f32_e32 v48, v176, v4
	v_add_f32_e32 v49, v176, v5
	v_max_f32_e32 v48, 0xc2a00000, v48
	v_max_f32_e32 v49, 0xc2a00000, v49
	v_mul_f32_e32 v48, 0xbfb8aa3b, v48
	v_mul_f32_e32 v49, 0xbfb8aa3b, v49
	v_exp_f32_e32 v48, v48
	v_exp_f32_e32 v49, v49
	v_add_f32_e32 v50, 1.0, v48
	v_add_f32_e32 v51, 1.0, v49
	v_rcp_f32_e32 v52, v50
	v_rcp_f32_e32 v53, v51
	v_fma_f32 v54, -v50, v52, 1.0
	v_fma_f32 v55, -v51, v53, 1.0
	v_fma_f32 v52, v52, v54, v52
	v_fma_f32 v53, v53, v55, v53
	ds_write_b32 v171, v52 offset:2048
	ds_write_b32 v171, v53 offset:2304
	v_add_f32_e32 v48, v176, v6
	v_add_f32_e32 v49, v176, v7
	v_max_f32_e32 v48, 0xc2a00000, v48
	v_max_f32_e32 v49, 0xc2a00000, v49
	v_mul_f32_e32 v48, 0xbfb8aa3b, v48
	v_mul_f32_e32 v49, 0xbfb8aa3b, v49
	v_exp_f32_e32 v48, v48
	v_exp_f32_e32 v49, v49
	v_add_f32_e32 v50, 1.0, v48
	v_add_f32_e32 v51, 1.0, v49
	v_rcp_f32_e32 v52, v50
	v_rcp_f32_e32 v53, v51
	v_fma_f32 v54, -v50, v52, 1.0
	v_fma_f32 v55, -v51, v53, 1.0
	v_fma_f32 v52, v52, v54, v52
	v_fma_f32 v53, v53, v55, v53
	ds_write_b32 v171, v52 offset:2560
	ds_write_b32 v171, v53 offset:2816
	v_add_f32_e32 v48, v176, v8
	v_add_f32_e32 v49, v176, v9
	v_max_f32_e32 v48, 0xc2a00000, v48
	v_max_f32_e32 v49, 0xc2a00000, v49
	v_mul_f32_e32 v48, 0xbfb8aa3b, v48
	v_mul_f32_e32 v49, 0xbfb8aa3b, v49
	v_exp_f32_e32 v48, v48
	v_exp_f32_e32 v49, v49
	v_add_f32_e32 v50, 1.0, v48
	v_add_f32_e32 v51, 1.0, v49
	v_rcp_f32_e32 v52, v50
	v_rcp_f32_e32 v53, v51
	v_fma_f32 v54, -v50, v52, 1.0
	v_fma_f32 v55, -v51, v53, 1.0
	v_fma_f32 v52, v52, v54, v52
	v_fma_f32 v53, v53, v55, v53
	ds_write_b32 v171, v52 offset:4096
	ds_write_b32 v171, v53 offset:4352
	v_add_f32_e32 v48, v176, v10
	v_add_f32_e32 v49, v176, v11
	v_max_f32_e32 v48, 0xc2a00000, v48
	v_max_f32_e32 v49, 0xc2a00000, v49
	v_mul_f32_e32 v48, 0xbfb8aa3b, v48
	v_mul_f32_e32 v49, 0xbfb8aa3b, v49
	v_exp_f32_e32 v48, v48
	v_exp_f32_e32 v49, v49
	v_add_f32_e32 v50, 1.0, v48
	v_add_f32_e32 v51, 1.0, v49
	v_rcp_f32_e32 v52, v50
	v_rcp_f32_e32 v53, v51
	v_fma_f32 v54, -v50, v52, 1.0
	v_fma_f32 v55, -v51, v53, 1.0
	v_fma_f32 v52, v52, v54, v52
	v_fma_f32 v53, v53, v55, v53
	ds_write_b32 v171, v52 offset:4608
	ds_write_b32 v171, v53 offset:4864
	v_add_f32_e32 v48, v176, v12
	v_add_f32_e32 v49, v176, v13
	v_max_f32_e32 v48, 0xc2a00000, v48
	v_max_f32_e32 v49, 0xc2a00000, v49
	v_mul_f32_e32 v48, 0xbfb8aa3b, v48
	v_mul_f32_e32 v49, 0xbfb8aa3b, v49
	v_exp_f32_e32 v48, v48
	v_exp_f32_e32 v49, v49
	v_add_f32_e32 v50, 1.0, v48
	v_add_f32_e32 v51, 1.0, v49
	v_rcp_f32_e32 v52, v50
	v_rcp_f32_e32 v53, v51
	v_fma_f32 v54, -v50, v52, 1.0
	v_fma_f32 v55, -v51, v53, 1.0
	v_fma_f32 v52, v52, v54, v52
	v_fma_f32 v53, v53, v55, v53
	ds_write_b32 v171, v52 offset:6144
	ds_write_b32 v171, v53 offset:6400
	v_add_f32_e32 v48, v176, v14
	v_add_f32_e32 v49, v176, v15
	v_max_f32_e32 v48, 0xc2a00000, v48
	v_max_f32_e32 v49, 0xc2a00000, v49
	v_mul_f32_e32 v48, 0xbfb8aa3b, v48
	v_mul_f32_e32 v49, 0xbfb8aa3b, v49
	v_exp_f32_e32 v48, v48
	v_exp_f32_e32 v49, v49
	v_add_f32_e32 v50, 1.0, v48
	v_add_f32_e32 v51, 1.0, v49
	v_rcp_f32_e32 v52, v50
	v_rcp_f32_e32 v53, v51
	v_fma_f32 v54, -v50, v52, 1.0
	v_fma_f32 v55, -v51, v53, 1.0
	v_fma_f32 v52, v52, v54, v52
	v_fma_f32 v53, v53, v55, v53
	ds_write_b32 v171, v52 offset:6656
	ds_write_b32 v171, v53 offset:6912
	s_branch .Lrw_p1_done
.Lrw_p1_decay:
	v_add_f32_e32 v48, v176, v0
	v_add_f32_e32 v49, v176, v1
	v_max_f32_e32 v48, 0xc2a00000, v48
	v_max_f32_e32 v49, 0xc2a00000, v49
	v_mul_f32_e32 v48, 0xbfb8aa3b, v48
	v_mul_f32_e32 v49, 0xbfb8aa3b, v49
	v_exp_f32_e32 v48, v48
	v_exp_f32_e32 v49, v49
	v_add_f32_e32 v50, 1.0, v48
	v_add_f32_e32 v51, 1.0, v49
	v_rcp_f32_e32 v52, v50
	v_rcp_f32_e32 v53, v51
	v_fma_f32 v54, -v50, v52, 1.0
	v_fma_f32 v55, -v51, v53, 1.0
	v_fma_f32 v52, v52, v54, v52
	v_fma_f32 v53, v53, v55, v53
	v_mul_f32_e32 v52, s43, v52
	v_mul_f32_e32 v53, s43, v53
	v_mul_f32_e32 v52, 0x3fb8aa3b, v52
	v_mul_f32_e32 v53, 0x3fb8aa3b, v53
	v_exp_f32_e32 v52, v52
	v_exp_f32_e32 v53, v53
	s_nop 0
	ds_write_b32 v171, v52
	ds_write_b32 v171, v53 offset:256
	v_add_f32_e32 v48, v176, v2
	v_add_f32_e32 v49, v176, v3
	v_max_f32_e32 v48, 0xc2a00000, v48
	v_max_f32_e32 v49, 0xc2a00000, v49
	v_mul_f32_e32 v48, 0xbfb8aa3b, v48
	v_mul_f32_e32 v49, 0xbfb8aa3b, v49
	v_exp_f32_e32 v48, v48
	v_exp_f32_e32 v49, v49
	v_add_f32_e32 v50, 1.0, v48
	v_add_f32_e32 v51, 1.0, v49
	v_rcp_f32_e32 v52, v50
	v_rcp_f32_e32 v53, v51
	v_fma_f32 v54, -v50, v52, 1.0
	v_fma_f32 v55, -v51, v53, 1.0
	v_fma_f32 v52, v52, v54, v52
	v_fma_f32 v53, v53, v55, v53
	v_mul_f32_e32 v52, s43, v52
	v_mul_f32_e32 v53, s43, v53
	v_mul_f32_e32 v52, 0x3fb8aa3b, v52
	v_mul_f32_e32 v53, 0x3fb8aa3b, v53
	v_exp_f32_e32 v52, v52
	v_exp_f32_e32 v53, v53
	s_nop 0
	ds_write_b32 v171, v52 offset:512
	ds_write_b32 v171, v53 offset:768
	v_add_f32_e32 v48, v176, v4
	v_add_f32_e32 v49, v176, v5
	v_max_f32_e32 v48, 0xc2a00000, v48
	v_max_f32_e32 v49, 0xc2a00000, v49
	v_mul_f32_e32 v48, 0xbfb8aa3b, v48
	v_mul_f32_e32 v49, 0xbfb8aa3b, v49
	v_exp_f32_e32 v48, v48
	v_exp_f32_e32 v49, v49
	v_add_f32_e32 v50, 1.0, v48
	v_add_f32_e32 v51, 1.0, v49
	v_rcp_f32_e32 v52, v50
	v_rcp_f32_e32 v53, v51
	v_fma_f32 v54, -v50, v52, 1.0
	v_fma_f32 v55, -v51, v53, 1.0
	v_fma_f32 v52, v52, v54, v52
	v_fma_f32 v53, v53, v55, v53
	v_mul_f32_e32 v52, s43, v52
	v_mul_f32_e32 v53, s43, v53
	v_mul_f32_e32 v52, 0x3fb8aa3b, v52
	v_mul_f32_e32 v53, 0x3fb8aa3b, v53
	v_exp_f32_e32 v52, v52
	v_exp_f32_e32 v53, v53
	s_nop 0
	ds_write_b32 v171, v52 offset:2048
	ds_write_b32 v171, v53 offset:2304
	v_add_f32_e32 v48, v176, v6
	v_add_f32_e32 v49, v176, v7
	v_max_f32_e32 v48, 0xc2a00000, v48
	v_max_f32_e32 v49, 0xc2a00000, v49
	v_mul_f32_e32 v48, 0xbfb8aa3b, v48
	v_mul_f32_e32 v49, 0xbfb8aa3b, v49
	v_exp_f32_e32 v48, v48
	v_exp_f32_e32 v49, v49
	v_add_f32_e32 v50, 1.0, v48
	v_add_f32_e32 v51, 1.0, v49
	v_rcp_f32_e32 v52, v50
	v_rcp_f32_e32 v53, v51
	v_fma_f32 v54, -v50, v52, 1.0
	v_fma_f32 v55, -v51, v53, 1.0
	v_fma_f32 v52, v52, v54, v52
	v_fma_f32 v53, v53, v55, v53
	v_mul_f32_e32 v52, s43, v52
	v_mul_f32_e32 v53, s43, v53
	v_mul_f32_e32 v52, 0x3fb8aa3b, v52
	v_mul_f32_e32 v53, 0x3fb8aa3b, v53
	v_exp_f32_e32 v52, v52
	v_exp_f32_e32 v53, v53
	s_nop 0
	ds_write_b32 v171, v52 offset:2560
	ds_write_b32 v171, v53 offset:2816
	v_add_f32_e32 v48, v176, v8
	v_add_f32_e32 v49, v176, v9
	v_max_f32_e32 v48, 0xc2a00000, v48
	v_max_f32_e32 v49, 0xc2a00000, v49
	v_mul_f32_e32 v48, 0xbfb8aa3b, v48
	v_mul_f32_e32 v49, 0xbfb8aa3b, v49
	v_exp_f32_e32 v48, v48
	v_exp_f32_e32 v49, v49
	v_add_f32_e32 v50, 1.0, v48
	v_add_f32_e32 v51, 1.0, v49
	v_rcp_f32_e32 v52, v50
	v_rcp_f32_e32 v53, v51
	v_fma_f32 v54, -v50, v52, 1.0
	v_fma_f32 v55, -v51, v53, 1.0
	v_fma_f32 v52, v52, v54, v52
	v_fma_f32 v53, v53, v55, v53
	v_mul_f32_e32 v52, s43, v52
	v_mul_f32_e32 v53, s43, v53
	v_mul_f32_e32 v52, 0x3fb8aa3b, v52
	v_mul_f32_e32 v53, 0x3fb8aa3b, v53
	v_exp_f32_e32 v52, v52
	v_exp_f32_e32 v53, v53
	s_nop 0
	ds_write_b32 v171, v52 offset:4096
	ds_write_b32 v171, v53 offset:4352
	v_add_f32_e32 v48, v176, v10
	v_add_f32_e32 v49, v176, v11
	v_max_f32_e32 v48, 0xc2a00000, v48
	v_max_f32_e32 v49, 0xc2a00000, v49
	v_mul_f32_e32 v48, 0xbfb8aa3b, v48
	v_mul_f32_e32 v49, 0xbfb8aa3b, v49
	v_exp_f32_e32 v48, v48
	v_exp_f32_e32 v49, v49
	v_add_f32_e32 v50, 1.0, v48
	v_add_f32_e32 v51, 1.0, v49
	v_rcp_f32_e32 v52, v50
	v_rcp_f32_e32 v53, v51
	v_fma_f32 v54, -v50, v52, 1.0
	v_fma_f32 v55, -v51, v53, 1.0
	v_fma_f32 v52, v52, v54, v52
	v_fma_f32 v53, v53, v55, v53
	v_mul_f32_e32 v52, s43, v52
	v_mul_f32_e32 v53, s43, v53
	v_mul_f32_e32 v52, 0x3fb8aa3b, v52
	v_mul_f32_e32 v53, 0x3fb8aa3b, v53
	v_exp_f32_e32 v52, v52
	v_exp_f32_e32 v53, v53
	s_nop 0
	ds_write_b32 v171, v52 offset:4608
	ds_write_b32 v171, v53 offset:4864
	v_add_f32_e32 v48, v176, v12
	v_add_f32_e32 v49, v176, v13
	v_max_f32_e32 v48, 0xc2a00000, v48
	v_max_f32_e32 v49, 0xc2a00000, v49
	v_mul_f32_e32 v48, 0xbfb8aa3b, v48
	v_mul_f32_e32 v49, 0xbfb8aa3b, v49
	v_exp_f32_e32 v48, v48
	v_exp_f32_e32 v49, v49
	v_add_f32_e32 v50, 1.0, v48
	v_add_f32_e32 v51, 1.0, v49
	v_rcp_f32_e32 v52, v50
	v_rcp_f32_e32 v53, v51
	v_fma_f32 v54, -v50, v52, 1.0
	v_fma_f32 v55, -v51, v53, 1.0
	v_fma_f32 v52, v52, v54, v52
	v_fma_f32 v53, v53, v55, v53
	v_mul_f32_e32 v52, s43, v52
	v_mul_f32_e32 v53, s43, v53
	v_mul_f32_e32 v52, 0x3fb8aa3b, v52
	v_mul_f32_e32 v53, 0x3fb8aa3b, v53
	v_exp_f32_e32 v52, v52
	v_exp_f32_e32 v53, v53
	s_nop 0
	ds_write_b32 v171, v52 offset:6144
	ds_write_b32 v171, v53 offset:6400
	v_add_f32_e32 v48, v176, v14
	v_add_f32_e32 v49, v176, v15
	v_max_f32_e32 v48, 0xc2a00000, v48
	v_max_f32_e32 v49, 0xc2a00000, v49
	v_mul_f32_e32 v48, 0xbfb8aa3b, v48
	v_mul_f32_e32 v49, 0xbfb8aa3b, v49
	v_exp_f32_e32 v48, v48
	v_exp_f32_e32 v49, v49
	v_add_f32_e32 v50, 1.0, v48
	v_add_f32_e32 v51, 1.0, v49
	v_rcp_f32_e32 v52, v50
	v_rcp_f32_e32 v53, v51
	v_fma_f32 v54, -v50, v52, 1.0
	v_fma_f32 v55, -v51, v53, 1.0
	v_fma_f32 v52, v52, v54, v52
	v_fma_f32 v53, v53, v55, v53
	v_mul_f32_e32 v52, s43, v52
	v_mul_f32_e32 v53, s43, v53
	v_mul_f32_e32 v52, 0x3fb8aa3b, v52
	v_mul_f32_e32 v53, 0x3fb8aa3b, v53
	v_exp_f32_e32 v52, v52
	v_exp_f32_e32 v53, v53
	s_nop 0
	ds_write_b32 v171, v52 offset:6656
	ds_write_b32 v171, v53 offset:6912
.Lrw_p1_done:
	s_waitcnt lgkmcnt(0)
	s_barrier
	s_lshl_b32 s38, s48, 5
	s_cmp_lt_u32 s48, 8
	s_cselect_b32 s36, 0xff, s44
	s_sub_i32 s39, s36, s38
	s_and_b64 s[36:37], s[28:29], exec
	s_cselect_b32 s49, s38, s39
	ds_read_b32 v48, v172 offset:24576
	ds_read_b32 v49, v162 offset:24576
	ds_read_b32 v50, v163 offset:24576
	ds_read_b32 v51, v164 offset:24576
	ds_read_b32 v52, v165 offset:24576
	ds_read_b32 v53, v166 offset:24576
	ds_read_b32 v54, v167 offset:24576
	ds_read_b32 v55, v168 offset:24576
	s_waitcnt vmcnt(0) lgkmcnt(0)
	v_lshlrev_b32_e32 v56, 16, v184
	v_lshlrev_b32_e32 v57, 16, v188
	v_lshlrev_b32_e32 v64, 16, v186
	v_lshlrev_b32_e32 v65, 16, v190
	v_add_f32_e32 v104, -1.0, v48
	v_add_f32_e32 v105, -1.0, v49
	v_fma_f32 v72, v174, v104, 1.0
	v_fma_f32 v73, v174, v105, 1.0
	v_mul_f32_e32 v80, v173, v56
	v_mul_f32_e32 v81, v173, v57
	v_mul_f32_e32 v72, v72, v56
	v_mul_f32_e32 v73, v73, v57
	v_mul_f32_e32 v88, v80, v80
	v_mul_f32_e32 v89, v81, v81
	v_mul_f32_e32 v96, v72, v64
	v_mul_f32_e32 v97, v73, v65
	v_mul_f32_e32 v96, v175, v96
	v_mul_f32_e32 v97, v175, v97
	v_add_f32_dpp v88, v88, v88 quad_perm:[1,0,3,2] row_mask:0xf bank_mask:0xf bound_ctrl:1
	v_add_f32_dpp v96, v96, v96 quad_perm:[1,0,3,2] row_mask:0xf bank_mask:0xf bound_ctrl:1
	v_add_f32_dpp v89, v89, v89 quad_perm:[1,0,3,2] row_mask:0xf bank_mask:0xf bound_ctrl:1
	v_add_f32_dpp v97, v97, v97 quad_perm:[1,0,3,2] row_mask:0xf bank_mask:0xf bound_ctrl:1
	v_add_f32_dpp v88, v88, v88 quad_perm:[2,3,0,1] row_mask:0xf bank_mask:0xf bound_ctrl:1
	v_add_f32_dpp v96, v96, v96 quad_perm:[2,3,0,1] row_mask:0xf bank_mask:0xf bound_ctrl:1
	v_add_f32_dpp v89, v89, v89 quad_perm:[2,3,0,1] row_mask:0xf bank_mask:0xf bound_ctrl:1
	v_add_f32_dpp v97, v97, v97 quad_perm:[2,3,0,1] row_mask:0xf bank_mask:0xf bound_ctrl:1
	v_add_f32_dpp v88, v88, v88 row_half_mirror row_mask:0xf bank_mask:0xf bound_ctrl:1
	v_add_f32_dpp v96, v96, v96 row_half_mirror row_mask:0xf bank_mask:0xf bound_ctrl:1
	v_add_f32_dpp v89, v89, v89 row_half_mirror row_mask:0xf bank_mask:0xf bound_ctrl:1
	v_add_f32_dpp v97, v97, v97 row_half_mirror row_mask:0xf bank_mask:0xf bound_ctrl:1
	v_add_f32_dpp v88, v88, v88 row_mirror row_mask:0xf bank_mask:0xf bound_ctrl:1
	v_add_f32_dpp v96, v96, v96 row_mirror row_mask:0xf bank_mask:0xf bound_ctrl:1
	v_add_f32_dpp v89, v89, v89 row_mirror row_mask:0xf bank_mask:0xf bound_ctrl:1
	v_add_f32_dpp v97, v97, v97 row_mirror row_mask:0xf bank_mask:0xf bound_ctrl:1
	v_add_f32_dpp v88, v88, v88 row_bcast:15 row_mask:0xa bank_mask:0xf
	v_add_f32_dpp v96, v96, v96 row_bcast:15 row_mask:0xa bank_mask:0xf
	v_add_f32_dpp v89, v89, v89 row_bcast:15 row_mask:0xa bank_mask:0xf
	v_add_f32_dpp v97, v97, v97 row_bcast:15 row_mask:0xa bank_mask:0xf
	v_add_f32_dpp v88, v88, v88 row_bcast:31 row_mask:0xc bank_mask:0xf
	v_add_f32_dpp v96, v96, v96 row_bcast:31 row_mask:0xc bank_mask:0xf
	v_add_f32_dpp v89, v89, v89 row_bcast:31 row_mask:0xc bank_mask:0xf
	v_add_f32_dpp v97, v97, v97 row_bcast:31 row_mask:0xc bank_mask:0xf
	v_readlane_b32 s50, v88, 63
	v_readlane_b32 s51, v89, 63
	v_readlane_b32 s64, v96, 63
	v_readlane_b32 s65, v97, 63
	s_max_u32 s50, s50, 0x179abe15
	s_max_u32 s51, s51, 0x179abe15
	v_rsq_f32_e32 v104, s50
	v_rsq_f32_e32 v105, s51
	v_lshlrev_b32_e32 v88, 16, v185
	v_lshlrev_b32_e32 v89, 16, v189
	v_mul_f32_e64 v80, v80, -v104
	v_mul_f32_e64 v81, v81, -v105
	v_mul_f32_e64 v96, v48, -v80
	v_mul_f32_e64 v97, v49, -v81
	ds_write2st64_b32 v172, v72, v80 offset0:32 offset1:64
	ds_write2st64_b32 v172, v96, v64 offset0:96 offset1:128
	ds_write_b32 v172, v88 offset:40960
	ds_write2st64_b32 v162, v73, v81 offset0:32 offset1:64
	ds_write2st64_b32 v162, v97, v65 offset0:96 offset1:128
	ds_write_b32 v162, v89 offset:40960
	v_lshlrev_b32_e32 v58, 16, v191
	v_lshlrev_b32_e32 v59, 16, v199
	v_lshlrev_b32_e32 v66, 16, v198
	v_lshlrev_b32_e32 v67, 16, v201
	v_add_f32_e32 v106, -1.0, v50
	v_add_f32_e32 v107, -1.0, v51
	v_fma_f32 v74, v174, v106, 1.0
	v_fma_f32 v75, v174, v107, 1.0
	v_mul_f32_e32 v82, v173, v58
	v_mul_f32_e32 v83, v173, v59
	v_mul_f32_e32 v74, v74, v58
	v_mul_f32_e32 v75, v75, v59
	v_mul_f32_e32 v90, v82, v82
	v_mul_f32_e32 v91, v83, v83
	v_mul_f32_e32 v98, v74, v66
	v_mul_f32_e32 v99, v75, v67
	v_mul_f32_e32 v98, v175, v98
	v_mul_f32_e32 v99, v175, v99
	v_add_f32_dpp v90, v90, v90 quad_perm:[1,0,3,2] row_mask:0xf bank_mask:0xf bound_ctrl:1
	v_add_f32_dpp v98, v98, v98 quad_perm:[1,0,3,2] row_mask:0xf bank_mask:0xf bound_ctrl:1
	v_add_f32_dpp v91, v91, v91 quad_perm:[1,0,3,2] row_mask:0xf bank_mask:0xf bound_ctrl:1
	v_add_f32_dpp v99, v99, v99 quad_perm:[1,0,3,2] row_mask:0xf bank_mask:0xf bound_ctrl:1
	v_add_f32_dpp v90, v90, v90 quad_perm:[2,3,0,1] row_mask:0xf bank_mask:0xf bound_ctrl:1
	v_add_f32_dpp v98, v98, v98 quad_perm:[2,3,0,1] row_mask:0xf bank_mask:0xf bound_ctrl:1
	v_add_f32_dpp v91, v91, v91 quad_perm:[2,3,0,1] row_mask:0xf bank_mask:0xf bound_ctrl:1
	v_add_f32_dpp v99, v99, v99 quad_perm:[2,3,0,1] row_mask:0xf bank_mask:0xf bound_ctrl:1
	v_add_f32_dpp v90, v90, v90 row_half_mirror row_mask:0xf bank_mask:0xf bound_ctrl:1
	v_add_f32_dpp v98, v98, v98 row_half_mirror row_mask:0xf bank_mask:0xf bound_ctrl:1
	v_add_f32_dpp v91, v91, v91 row_half_mirror row_mask:0xf bank_mask:0xf bound_ctrl:1
	v_add_f32_dpp v99, v99, v99 row_half_mirror row_mask:0xf bank_mask:0xf bound_ctrl:1
	v_add_f32_dpp v90, v90, v90 row_mirror row_mask:0xf bank_mask:0xf bound_ctrl:1
	v_add_f32_dpp v98, v98, v98 row_mirror row_mask:0xf bank_mask:0xf bound_ctrl:1
	v_add_f32_dpp v91, v91, v91 row_mirror row_mask:0xf bank_mask:0xf bound_ctrl:1
	v_add_f32_dpp v99, v99, v99 row_mirror row_mask:0xf bank_mask:0xf bound_ctrl:1
	v_add_f32_dpp v90, v90, v90 row_bcast:15 row_mask:0xa bank_mask:0xf
	v_add_f32_dpp v98, v98, v98 row_bcast:15 row_mask:0xa bank_mask:0xf
	v_add_f32_dpp v91, v91, v91 row_bcast:15 row_mask:0xa bank_mask:0xf
	v_add_f32_dpp v99, v99, v99 row_bcast:15 row_mask:0xa bank_mask:0xf
	v_add_f32_dpp v90, v90, v90 row_bcast:31 row_mask:0xc bank_mask:0xf
	v_add_f32_dpp v98, v98, v98 row_bcast:31 row_mask:0xc bank_mask:0xf
	v_add_f32_dpp v91, v91, v91 row_bcast:31 row_mask:0xc bank_mask:0xf
	v_add_f32_dpp v99, v99, v99 row_bcast:31 row_mask:0xc bank_mask:0xf
	v_readlane_b32 s50, v90, 63
	v_readlane_b32 s51, v91, 63
	v_readlane_b32 s66, v98, 63
	v_readlane_b32 s67, v99, 63
	s_max_u32 s50, s50, 0x179abe15
	s_max_u32 s51, s51, 0x179abe15
	v_rsq_f32_e32 v106, s50
	v_rsq_f32_e32 v107, s51
	v_lshlrev_b32_e32 v90, 16, v192
	v_lshlrev_b32_e32 v91, 16, v200
	v_mul_f32_e64 v82, v82, -v106
	v_mul_f32_e64 v83, v83, -v107
	v_mul_f32_e64 v98, v50, -v82
	v_mul_f32_e64 v99, v51, -v83
	ds_write2st64_b32 v163, v74, v82 offset0:32 offset1:64
	ds_write2st64_b32 v163, v98, v66 offset0:96 offset1:128
	ds_write_b32 v163, v90 offset:40960
	ds_write2st64_b32 v164, v75, v83 offset0:32 offset1:64
	ds_write2st64_b32 v164, v99, v67 offset0:96 offset1:128
	ds_write_b32 v164, v91 offset:40960
	v_lshlrev_b32_e32 v60, 16, v202
	v_lshlrev_b32_e32 v61, 16, v205
	v_lshlrev_b32_e32 v68, 16, v204
	v_lshlrev_b32_e32 v69, 16, v207
	v_add_f32_e32 v108, -1.0, v52
	v_add_f32_e32 v109, -1.0, v53
	v_fma_f32 v76, v174, v108, 1.0
	v_fma_f32 v77, v174, v109, 1.0
	v_mul_f32_e32 v84, v173, v60
	v_mul_f32_e32 v85, v173, v61
	v_mul_f32_e32 v76, v76, v60
	v_mul_f32_e32 v77, v77, v61
	v_mul_f32_e32 v92, v84, v84
	v_mul_f32_e32 v93, v85, v85
	v_mul_f32_e32 v100, v76, v68
	v_mul_f32_e32 v101, v77, v69
	v_mul_f32_e32 v100, v175, v100
	v_mul_f32_e32 v101, v175, v101
	v_add_f32_dpp v92, v92, v92 quad_perm:[1,0,3,2] row_mask:0xf bank_mask:0xf bound_ctrl:1
	v_add_f32_dpp v100, v100, v100 quad_perm:[1,0,3,2] row_mask:0xf bank_mask:0xf bound_ctrl:1
	v_add_f32_dpp v93, v93, v93 quad_perm:[1,0,3,2] row_mask:0xf bank_mask:0xf bound_ctrl:1
	v_add_f32_dpp v101, v101, v101 quad_perm:[1,0,3,2] row_mask:0xf bank_mask:0xf bound_ctrl:1
	v_add_f32_dpp v92, v92, v92 quad_perm:[2,3,0,1] row_mask:0xf bank_mask:0xf bound_ctrl:1
	v_add_f32_dpp v100, v100, v100 quad_perm:[2,3,0,1] row_mask:0xf bank_mask:0xf bound_ctrl:1
	v_add_f32_dpp v93, v93, v93 quad_perm:[2,3,0,1] row_mask:0xf bank_mask:0xf bound_ctrl:1
	v_add_f32_dpp v101, v101, v101 quad_perm:[2,3,0,1] row_mask:0xf bank_mask:0xf bound_ctrl:1
	v_add_f32_dpp v92, v92, v92 row_half_mirror row_mask:0xf bank_mask:0xf bound_ctrl:1
	v_add_f32_dpp v100, v100, v100 row_half_mirror row_mask:0xf bank_mask:0xf bound_ctrl:1
	v_add_f32_dpp v93, v93, v93 row_half_mirror row_mask:0xf bank_mask:0xf bound_ctrl:1
	v_add_f32_dpp v101, v101, v101 row_half_mirror row_mask:0xf bank_mask:0xf bound_ctrl:1
	v_add_f32_dpp v92, v92, v92 row_mirror row_mask:0xf bank_mask:0xf bound_ctrl:1
	v_add_f32_dpp v100, v100, v100 row_mirror row_mask:0xf bank_mask:0xf bound_ctrl:1
	v_add_f32_dpp v93, v93, v93 row_mirror row_mask:0xf bank_mask:0xf bound_ctrl:1
	v_add_f32_dpp v101, v101, v101 row_mirror row_mask:0xf bank_mask:0xf bound_ctrl:1
	v_add_f32_dpp v92, v92, v92 row_bcast:15 row_mask:0xa bank_mask:0xf
	v_add_f32_dpp v100, v100, v100 row_bcast:15 row_mask:0xa bank_mask:0xf
	v_add_f32_dpp v93, v93, v93 row_bcast:15 row_mask:0xa bank_mask:0xf
	v_add_f32_dpp v101, v101, v101 row_bcast:15 row_mask:0xa bank_mask:0xf
	v_add_f32_dpp v92, v92, v92 row_bcast:31 row_mask:0xc bank_mask:0xf
	v_add_f32_dpp v100, v100, v100 row_bcast:31 row_mask:0xc bank_mask:0xf
	v_add_f32_dpp v93, v93, v93 row_bcast:31 row_mask:0xc bank_mask:0xf
	v_add_f32_dpp v101, v101, v101 row_bcast:31 row_mask:0xc bank_mask:0xf
	v_readlane_b32 s50, v92, 63
	v_readlane_b32 s51, v93, 63
	v_readlane_b32 s68, v100, 63
	v_readlane_b32 s69, v101, 63
	s_max_u32 s50, s50, 0x179abe15
	s_max_u32 s51, s51, 0x179abe15
	v_rsq_f32_e32 v108, s50
	v_rsq_f32_e32 v109, s51
	v_lshlrev_b32_e32 v92, 16, v203
	v_lshlrev_b32_e32 v93, 16, v206
	v_mul_f32_e64 v84, v84, -v108
	v_mul_f32_e64 v85, v85, -v109
	v_mul_f32_e64 v100, v52, -v84
	v_mul_f32_e64 v101, v53, -v85
	ds_write2st64_b32 v165, v76, v84 offset0:32 offset1:64
	ds_write2st64_b32 v165, v100, v68 offset0:96 offset1:128
	ds_write_b32 v165, v92 offset:40960
	ds_write2st64_b32 v166, v77, v85 offset0:32 offset1:64
	ds_write2st64_b32 v166, v101, v69 offset0:96 offset1:128
	ds_write_b32 v166, v93 offset:40960
	v_lshlrev_b32_e32 v62, 16, v208
	v_lshlrev_b32_e32 v63, 16, v211
	v_lshlrev_b32_e32 v70, 16, v210
	v_lshlrev_b32_e32 v71, 16, v213
	v_add_f32_e32 v110, -1.0, v54
	v_add_f32_e32 v111, -1.0, v55
	v_fma_f32 v78, v174, v110, 1.0
	v_fma_f32 v79, v174, v111, 1.0
	v_mul_f32_e32 v86, v173, v62
	v_mul_f32_e32 v87, v173, v63
	v_mul_f32_e32 v78, v78, v62
	v_mul_f32_e32 v79, v79, v63
	v_mul_f32_e32 v94, v86, v86
	v_mul_f32_e32 v95, v87, v87
	v_mul_f32_e32 v102, v78, v70
	v_mul_f32_e32 v103, v79, v71
	v_mul_f32_e32 v102, v175, v102
	v_mul_f32_e32 v103, v175, v103
	v_add_f32_dpp v94, v94, v94 quad_perm:[1,0,3,2] row_mask:0xf bank_mask:0xf bound_ctrl:1
	v_add_f32_dpp v102, v102, v102 quad_perm:[1,0,3,2] row_mask:0xf bank_mask:0xf bound_ctrl:1
	v_add_f32_dpp v95, v95, v95 quad_perm:[1,0,3,2] row_mask:0xf bank_mask:0xf bound_ctrl:1
	v_add_f32_dpp v103, v103, v103 quad_perm:[1,0,3,2] row_mask:0xf bank_mask:0xf bound_ctrl:1
	v_add_f32_dpp v94, v94, v94 quad_perm:[2,3,0,1] row_mask:0xf bank_mask:0xf bound_ctrl:1
	v_add_f32_dpp v102, v102, v102 quad_perm:[2,3,0,1] row_mask:0xf bank_mask:0xf bound_ctrl:1
	v_add_f32_dpp v95, v95, v95 quad_perm:[2,3,0,1] row_mask:0xf bank_mask:0xf bound_ctrl:1
	v_add_f32_dpp v103, v103, v103 quad_perm:[2,3,0,1] row_mask:0xf bank_mask:0xf bound_ctrl:1
	v_add_f32_dpp v94, v94, v94 row_half_mirror row_mask:0xf bank_mask:0xf bound_ctrl:1
	v_add_f32_dpp v102, v102, v102 row_half_mirror row_mask:0xf bank_mask:0xf bound_ctrl:1
	v_add_f32_dpp v95, v95, v95 row_half_mirror row_mask:0xf bank_mask:0xf bound_ctrl:1
	v_add_f32_dpp v103, v103, v103 row_half_mirror row_mask:0xf bank_mask:0xf bound_ctrl:1
	v_add_f32_dpp v94, v94, v94 row_mirror row_mask:0xf bank_mask:0xf bound_ctrl:1
	v_add_f32_dpp v102, v102, v102 row_mirror row_mask:0xf bank_mask:0xf bound_ctrl:1
	v_add_f32_dpp v95, v95, v95 row_mirror row_mask:0xf bank_mask:0xf bound_ctrl:1
	v_add_f32_dpp v103, v103, v103 row_mirror row_mask:0xf bank_mask:0xf bound_ctrl:1
	v_add_f32_dpp v94, v94, v94 row_bcast:15 row_mask:0xa bank_mask:0xf
	v_add_f32_dpp v102, v102, v102 row_bcast:15 row_mask:0xa bank_mask:0xf
	v_add_f32_dpp v95, v95, v95 row_bcast:15 row_mask:0xa bank_mask:0xf
	v_add_f32_dpp v103, v103, v103 row_bcast:15 row_mask:0xa bank_mask:0xf
	v_add_f32_dpp v94, v94, v94 row_bcast:31 row_mask:0xc bank_mask:0xf
	v_add_f32_dpp v102, v102, v102 row_bcast:31 row_mask:0xc bank_mask:0xf
	v_add_f32_dpp v95, v95, v95 row_bcast:31 row_mask:0xc bank_mask:0xf
	v_add_f32_dpp v103, v103, v103 row_bcast:31 row_mask:0xc bank_mask:0xf
	v_readlane_b32 s50, v94, 63
	v_readlane_b32 s51, v95, 63
	v_readlane_b32 s70, v102, 63
	v_readlane_b32 s71, v103, 63
	s_max_u32 s50, s50, 0x179abe15
	s_max_u32 s51, s51, 0x179abe15
	v_rsq_f32_e32 v110, s50
	v_rsq_f32_e32 v111, s51
	v_lshlrev_b32_e32 v94, 16, v209
	v_lshlrev_b32_e32 v95, 16, v212
	v_mul_f32_e64 v86, v86, -v110
	v_mul_f32_e64 v87, v87, -v111
	v_mul_f32_e64 v102, v54, -v86
	v_mul_f32_e64 v103, v55, -v87
	ds_write2st64_b32 v167, v78, v86 offset0:32 offset1:64
	ds_write2st64_b32 v167, v102, v70 offset0:96 offset1:128
	ds_write_b32 v167, v94 offset:40960
	ds_write2st64_b32 v168, v79, v87 offset0:32 offset1:64
	ds_write2st64_b32 v168, v103, v71 offset0:96 offset1:128
	ds_write_b32 v168, v95 offset:40960
	v_writelane_b32 v1, s64, 0
	v_writelane_b32 v1, s65, 1
	v_writelane_b32 v1, s66, 2
	v_writelane_b32 v1, s67, 3
	v_writelane_b32 v1, s68, 4
	v_writelane_b32 v1, s69, 5
	v_writelane_b32 v1, s70, 6
	v_writelane_b32 v1, s71, 7
	v_lshl_add_u32 v4, v194, 2, v195
	v_add_u32_e32 v4, s49, v4
	v_ashrrev_i32_e32 v5, 31, v4
	v_lshl_add_u64 v[4:5], s[30:31], 0, v[4:5]
	v_lshlrev_b64 v[4:5], 6, v[4:5]
	v_lshl_add_u64 v[4:5], s[34:35], 0, v[4:5]
	s_mov_b64 exec, 0xff
	global_store_dword v[4:5], v1, off
	s_mov_b64 exec, -1
	s_add_i32 s50, s48, 1
	s_cmpk_eq_i32 s48, 0x47
	s_waitcnt lgkmcnt(0)
	s_barrier
	s_cbranch_scc1 .LBB0_1682
	s_lshl_b32 s38, s50, 5
	s_cmp_lt_u32 s48, 7
	s_cselect_b32 s36, 0xff, s44
	s_sub_i32 s39, s36, s38
	s_and_b64 s[36:37], s[28:29], exec
	s_cselect_b32 s36, s38, s39
	v_add_u32_e32 v0, s36, v194
	v_ashrrev_i32_e32 v1, 31, v0
	v_lshl_add_u64 v[0:1], v[0:1], 0, s[24:25]
	v_lshlrev_b64 v[0:1], 8, v[0:1]
	v_lshl_add_u64 v[0:1], v[126:127], 0, v[0:1]
	global_load_dwordx4 v[32:35], v[0:1], off
	global_load_dwordx4 v[36:39], v[0:1], off offset:32
	global_load_dwordx4 v[40:43], v[0:1], off offset:64
	global_load_dwordx4 v[44:47], v[0:1], off offset:96
	v_add_u32_e32 v0, s36, v195
	v_add_u32_e32 v6, s36, v177
	v_ashrrev_i32_e32 v1, 31, v0
	v_ashrrev_i32_e32 v7, 31, v6
	v_add_u32_e32 v12, s36, v178
	v_lshl_add_u64 v[0:1], v[0:1], 0, s[24:25]
	v_lshl_add_u64 v[6:7], v[6:7], 0, s[24:25]
	v_ashrrev_i32_e32 v13, 31, v12
	v_lshlrev_b64 v[0:1], 11, v[0:1]
	v_lshlrev_b64 v[6:7], 11, v[6:7]
	v_lshl_add_u64 v[12:13], v[12:13], 0, s[24:25]
	v_or_b32_e32 v0, v0, v197
	v_or_b32_e32 v6, v6, v197
	v_lshlrev_b64 v[12:13], 11, v[12:13]
	v_lshl_add_u64 v[2:3], s[20:21], 0, v[0:1]
	v_lshl_add_u64 v[8:9], s[20:21], 0, v[6:7]
	v_or_b32_e32 v12, v12, v197
	v_lshl_add_u64 v[4:5], s[22:23], 0, v[0:1]
	v_lshl_add_u64 v[0:1], s[18:19], 0, v[0:1]
	v_lshl_add_u64 v[10:11], s[22:23], 0, v[6:7]
	v_lshl_add_u64 v[6:7], s[18:19], 0, v[6:7]
	v_lshl_add_u64 v[14:15], s[20:21], 0, v[12:13]
	v_lshl_add_u64 v[48:49], s[22:23], 0, v[12:13]
	global_load_ushort v184, v[2:3], off
	global_load_ushort v185, v[4:5], off
	global_load_ushort v186, v[0:1], off
	global_load_ushort v188, v[8:9], off
	global_load_ushort v189, v[10:11], off
	global_load_ushort v190, v[6:7], off
	global_load_ushort v191, v[14:15], off
	global_load_ushort v192, v[48:49], off
	v_add_u32_e32 v2, s36, v179
	v_add_u32_e32 v8, s36, v182
	v_ashrrev_i32_e32 v3, 31, v2
	v_ashrrev_i32_e32 v9, 31, v8
	v_add_u32_e32 v14, s36, v183
	v_lshl_add_u64 v[2:3], v[2:3], 0, s[24:25]
	v_lshl_add_u64 v[8:9], v[8:9], 0, s[24:25]
	v_ashrrev_i32_e32 v15, 31, v14
	v_lshlrev_b64 v[2:3], 11, v[2:3]
	v_lshlrev_b64 v[8:9], 11, v[8:9]
	v_lshl_add_u64 v[14:15], v[14:15], 0, s[24:25]
	v_or_b32_e32 v2, v2, v197
	v_or_b32_e32 v8, v8, v197
	v_lshlrev_b64 v[14:15], 11, v[14:15]
	v_lshl_add_u64 v[0:1], s[18:19], 0, v[12:13]
	v_lshl_add_u64 v[4:5], s[20:21], 0, v[2:3]
	v_lshl_add_u64 v[10:11], s[20:21], 0, v[8:9]
	v_or_b32_e32 v14, v14, v197
	v_lshl_add_u64 v[6:7], s[22:23], 0, v[2:3]
	v_lshl_add_u64 v[2:3], s[18:19], 0, v[2:3]
	v_lshl_add_u64 v[12:13], s[22:23], 0, v[8:9]
	v_lshl_add_u64 v[8:9], s[18:19], 0, v[8:9]
	v_lshl_add_u64 v[48:49], s[20:21], 0, v[14:15]
	global_load_ushort v198, v[0:1], off
	global_load_ushort v199, v[4:5], off
	global_load_ushort v200, v[6:7], off
	global_load_ushort v201, v[2:3], off
	global_load_ushort v202, v[10:11], off
	global_load_ushort v203, v[12:13], off
	global_load_ushort v204, v[8:9], off
	global_load_ushort v205, v[48:49], off
	v_add_u32_e32 v4, s36, v187
	v_add_u32_e32 v10, s36, v193
	v_ashrrev_i32_e32 v5, 31, v4
	v_ashrrev_i32_e32 v11, 31, v10
	v_lshl_add_u64 v[4:5], v[4:5], 0, s[24:25]
	v_lshl_add_u64 v[10:11], v[10:11], 0, s[24:25]
	v_lshlrev_b64 v[4:5], 11, v[4:5]
	v_lshlrev_b64 v[10:11], 11, v[10:11]
	v_lshl_add_u64 v[0:1], s[22:23], 0, v[14:15]
	v_or_b32_e32 v4, v4, v197
	v_or_b32_e32 v10, v10, v197
	v_lshl_add_u64 v[2:3], s[18:19], 0, v[14:15]
	v_lshl_add_u64 v[6:7], s[20:21], 0, v[4:5]
	v_lshl_add_u64 v[8:9], s[22:23], 0, v[4:5]
	v_lshl_add_u64 v[4:5], s[18:19], 0, v[4:5]
	v_lshl_add_u64 v[12:13], s[20:21], 0, v[10:11]
	v_lshl_add_u64 v[14:15], s[22:23], 0, v[10:11]
	v_lshl_add_u64 v[10:11], s[18:19], 0, v[10:11]
	global_load_ushort v206, v[0:1], off
	global_load_ushort v207, v[2:3], off
	global_load_ushort v208, v[6:7], off
	global_load_ushort v209, v[8:9], off
	global_load_ushort v210, v[4:5], off
	global_load_ushort v211, v[12:13], off
	global_load_ushort v212, v[14:15], off
	global_load_ushort v213, v[10:11], off
